# v112 + attention unit epilogue bf16 row stores in saddr form (128 per wave-unit)
# baseline (speedup 1.0000x reference)
.LBB0_521:
	v_mov_b32_e32 v129, v144
	s_nop 1
	v_permlane32_swap_b32_e32 v144, v129
	v_add_f32_e32 v144, v144, v129
	s_and_saveexec_b64 s[4:5], s[0:1]
	ds_write_b32 v226, v144
	s_or_b64 exec, exec, s[4:5]
	s_waitcnt lgkmcnt(0)
	v_add_u32_e32 v136, s21, v210
	ds_read_b128 v[128:131], v136
	ds_read_b128 v[132:135], v136 offset:32
	s_ashr_i32 s21, s20, 31
	s_lshl_b64 s[0:1], s[20:21], 12
	ds_read_b128 v[138:141], v136 offset:96
	s_waitcnt lgkmcnt(2)
	v_rcp_f32_e32 v142, v128
	v_rcp_f32_e32 v145, v129
	v_rcp_f32_e32 v152, v130
	v_rcp_f32_e32 v161, v131
	ds_read_b128 v[128:131], v136 offset:64
	s_waitcnt lgkmcnt(2)
	v_rcp_f32_e32 v162, v132
	v_rcp_f32_e32 v163, v133
	v_rcp_f32_e32 v164, v134
	v_rcp_f32_e32 v165, v135
	s_waitcnt lgkmcnt(0)
	v_rcp_f32_e32 v137, v128
	v_rcp_f32_e32 v136, v129
	v_rcp_f32_e32 v135, v130
	v_rcp_f32_e32 v134, v131
	v_rcp_f32_e32 v133, v138
	v_rcp_f32_e32 v132, v139
	v_rcp_f32_e32 v131, v140
	v_rcp_f32_e32 v130, v141
	s_add_u32 s0, s62, s0
	s_addc_u32 s1, s63, s1
	s_mov_b64 s[4:5], -1
	s_andn2_b64 vcc, exec, s[18:19]
	v_lshlrev_b32_e32 v210, 2, v219
	v_lshlrev_b32_e32 v128, 14, v218
	v_lshl_add_u32 v129, v218, 5, v219
	v_lshlrev_b32_e32 v128, 4, v129
	s_mov_b32 s96, s0
	s_mov_b32 s97, s1
	s_cbranch_vccnz .Lepi0_p0
	s_lshl_b64 s[4:5], s[20:21], 11
	s_add_u32 s4, s64, s4
	s_addc_u32 s5, s65, s5
	v_lshlrev_b32_e32 v140, 1, v219
	v_lshl_add_u32 v140, v218, 13, v140
	v_mov_b32_e32 v141, 0
	s_nop 0
	s_mov_b64 s[100:101], 0x1000
	s_mov_b64 s[98:99], 0x4000
	global_load_dwordx4 v[166:169], v128, s[96:97]
	s_add_u32 s96, s96, 0x1000
	s_addc_u32 s97, s97, 0
	global_load_dwordx4 v[170:173], v128, s[96:97]
	s_add_u32 s96, s96, 0x1000
	s_addc_u32 s97, s97, 0
	global_load_dwordx4 v[174:177], v128, s[96:97]
	s_add_u32 s96, s96, 0x1000
	s_addc_u32 s97, s97, 0
	global_load_dwordx4 v[178:181], v128, s[96:97]
	s_add_u32 s96, s96, 0x1000
	s_addc_u32 s97, s97, 0
	global_load_dwordx4 v[182:185], v128, s[96:97]
	s_add_u32 s96, s96, 0x1000
	s_addc_u32 s97, s97, 0
	global_load_dwordx4 v[186:189], v128, s[96:97]
	s_add_u32 s96, s96, 0x1000
	s_addc_u32 s97, s97, 0
	global_load_dwordx4 v[190:193], v128, s[96:97]
	s_add_u32 s96, s96, 0x1000
	s_addc_u32 s97, s97, 0
	global_load_dwordx4 v[194:197], v128, s[96:97]
	s_add_u32 s96, s96, 0x1000
	s_addc_u32 s97, s97, 0
	global_load_dwordx4 v[198:201], v128, s[96:97]
	s_add_u32 s96, s96, 0x1000
	s_addc_u32 s97, s97, 0
	global_load_dwordx4 v[202:205], v128, s[96:97]
	s_add_u32 s96, s96, 0x1000
	s_addc_u32 s97, s97, 0
	global_load_dwordx4 v[240:243], v128, s[96:97]
	s_add_u32 s96, s96, 0x1000
	s_addc_u32 s97, s97, 0
	global_load_dwordx4 v[244:247], v128, s[96:97]
	s_add_u32 s96, s96, 0x1000
	s_addc_u32 s97, s97, 0
	global_load_dwordx4 v[248:251], v128, s[96:97]
	s_add_u32 s96, s96, 0x1000
	s_addc_u32 s97, s97, 0
	global_load_dwordx4 v[252:255], v128, s[96:97]
	s_add_u32 s96, s96, 0x1000
	s_addc_u32 s97, s97, 0
	global_load_dwordx4 v[232:235], v128, s[96:97]
	s_add_u32 s96, s96, 0x1000
	s_addc_u32 s97, s97, 0
	global_load_dwordx4 v[154:157], v128, s[96:97]
	s_add_u32 s96, s96, 0x1000
	s_addc_u32 s97, s97, 0
	s_waitcnt vmcnt(8)
	v_add_u32_e32 v141, 0x1000, v140
	v_mul_f32_e32 v158, v0, v142
	v_fma_f32 v166, -v209, v158, v166
	v_bfe_u32 v158, v166, 16, 1
	v_add3_u32 v166, v166, v158, s39
	global_store_short_d16_hi v140, v166, s[4:5]
	v_mul_f32_e32 v159, v1, v145
	v_fma_f32 v167, -v209, v159, v167
	v_bfe_u32 v159, v167, 16, 1
	v_add3_u32 v167, v167, v159, s39
	global_store_short_d16_hi v140, v167, s[4:5] offset:2048
	v_mul_f32_e32 v160, v2, v152
	v_fma_f32 v168, -v209, v160, v168
	v_bfe_u32 v160, v168, 16, 1
	v_add3_u32 v168, v168, v160, s39
	global_store_short_d16_hi v141, v168, s[4:5]
	v_mul_f32_e32 v150, v3, v161
	v_fma_f32 v169, -v209, v150, v169
	v_bfe_u32 v150, v169, 16, 1
	v_add3_u32 v169, v169, v150, s39
	global_store_short_d16_hi v141, v169, s[4:5] offset:2048
	v_mul_f32_e32 v158, v112, v142
	v_fma_f32 v170, -v209, v158, v170
	v_bfe_u32 v158, v170, 16, 1
	v_add3_u32 v170, v170, v158, s39
	global_store_short_d16_hi v140, v170, s[4:5] offset:64
	v_mul_f32_e32 v159, v113, v145
	v_fma_f32 v171, -v209, v159, v171
	v_bfe_u32 v159, v171, 16, 1
	v_add3_u32 v171, v171, v159, s39
	global_store_short_d16_hi v140, v171, s[4:5] offset:2112
	v_mul_f32_e32 v160, v114, v152
	v_fma_f32 v172, -v209, v160, v172
	v_bfe_u32 v160, v172, 16, 1
	v_add3_u32 v172, v172, v160, s39
	global_store_short_d16_hi v141, v172, s[4:5] offset:64
	v_mul_f32_e32 v150, v115, v161
	v_fma_f32 v173, -v209, v150, v173
	v_bfe_u32 v150, v173, 16, 1
	v_add3_u32 v173, v173, v150, s39
	global_store_short_d16_hi v141, v173, s[4:5] offset:2112
	v_mul_f32_e32 v158, v96, v142
	v_fma_f32 v174, -v209, v158, v174
	v_bfe_u32 v158, v174, 16, 1
	v_add3_u32 v174, v174, v158, s39
	global_store_short_d16_hi v140, v174, s[4:5] offset:128
	v_mul_f32_e32 v159, v97, v145
	v_fma_f32 v175, -v209, v159, v175
	v_bfe_u32 v159, v175, 16, 1
	v_add3_u32 v175, v175, v159, s39
	global_store_short_d16_hi v140, v175, s[4:5] offset:2176
	v_mul_f32_e32 v160, v98, v152
	v_fma_f32 v176, -v209, v160, v176
	v_bfe_u32 v160, v176, 16, 1
	v_add3_u32 v176, v176, v160, s39
	global_store_short_d16_hi v141, v176, s[4:5] offset:128
	v_mul_f32_e32 v150, v99, v161
	v_fma_f32 v177, -v209, v150, v177
	v_bfe_u32 v150, v177, 16, 1
	v_add3_u32 v177, v177, v150, s39
	global_store_short_d16_hi v141, v177, s[4:5] offset:2176
	v_mul_f32_e32 v158, v80, v142
	v_fma_f32 v178, -v209, v158, v178
	v_bfe_u32 v158, v178, 16, 1
	v_add3_u32 v178, v178, v158, s39
	global_store_short_d16_hi v140, v178, s[4:5] offset:192
	v_mul_f32_e32 v159, v81, v145
	v_fma_f32 v179, -v209, v159, v179
	v_bfe_u32 v159, v179, 16, 1
	v_add3_u32 v179, v179, v159, s39
	global_store_short_d16_hi v140, v179, s[4:5] offset:2240
	v_mul_f32_e32 v160, v82, v152
	v_fma_f32 v180, -v209, v160, v180
	v_bfe_u32 v160, v180, 16, 1
	v_add3_u32 v180, v180, v160, s39
	global_store_short_d16_hi v141, v180, s[4:5] offset:192
	v_mul_f32_e32 v150, v83, v161
	v_fma_f32 v181, -v209, v150, v181
	v_bfe_u32 v150, v181, 16, 1
	v_add3_u32 v181, v181, v150, s39
	global_store_short_d16_hi v141, v181, s[4:5] offset:2240
	v_mul_f32_e32 v158, v64, v142
	v_fma_f32 v182, -v209, v158, v182
	v_bfe_u32 v158, v182, 16, 1
	v_add3_u32 v182, v182, v158, s39
	global_store_short_d16_hi v140, v182, s[4:5] offset:256
	v_mul_f32_e32 v159, v65, v145
	v_fma_f32 v183, -v209, v159, v183
	v_bfe_u32 v159, v183, 16, 1
	v_add3_u32 v183, v183, v159, s39
	global_store_short_d16_hi v140, v183, s[4:5] offset:2304
	v_mul_f32_e32 v160, v66, v152
	v_fma_f32 v184, -v209, v160, v184
	v_bfe_u32 v160, v184, 16, 1
	v_add3_u32 v184, v184, v160, s39
	global_store_short_d16_hi v141, v184, s[4:5] offset:256
	v_mul_f32_e32 v150, v67, v161
	v_fma_f32 v185, -v209, v150, v185
	v_bfe_u32 v150, v185, 16, 1
	v_add3_u32 v185, v185, v150, s39
	global_store_short_d16_hi v141, v185, s[4:5] offset:2304
	v_mul_f32_e32 v158, v48, v142
	v_fma_f32 v186, -v209, v158, v186
	v_bfe_u32 v158, v186, 16, 1
	v_add3_u32 v186, v186, v158, s39
	global_store_short_d16_hi v140, v186, s[4:5] offset:320
	v_mul_f32_e32 v159, v49, v145
	v_fma_f32 v187, -v209, v159, v187
	v_bfe_u32 v159, v187, 16, 1
	v_add3_u32 v187, v187, v159, s39
	global_store_short_d16_hi v140, v187, s[4:5] offset:2368
	v_mul_f32_e32 v160, v50, v152
	v_fma_f32 v188, -v209, v160, v188
	v_bfe_u32 v160, v188, 16, 1
	v_add3_u32 v188, v188, v160, s39
	global_store_short_d16_hi v141, v188, s[4:5] offset:320
	v_mul_f32_e32 v150, v51, v161
	v_fma_f32 v189, -v209, v150, v189
	v_bfe_u32 v150, v189, 16, 1
	v_add3_u32 v189, v189, v150, s39
	global_store_short_d16_hi v141, v189, s[4:5] offset:2368
	v_mul_f32_e32 v158, v32, v142
	v_fma_f32 v190, -v209, v158, v190
	v_bfe_u32 v158, v190, 16, 1
	v_add3_u32 v190, v190, v158, s39
	global_store_short_d16_hi v140, v190, s[4:5] offset:384
	v_mul_f32_e32 v159, v33, v145
	v_fma_f32 v191, -v209, v159, v191
	v_bfe_u32 v159, v191, 16, 1
	v_add3_u32 v191, v191, v159, s39
	global_store_short_d16_hi v140, v191, s[4:5] offset:2432
	v_mul_f32_e32 v160, v34, v152
	v_fma_f32 v192, -v209, v160, v192
	v_bfe_u32 v160, v192, 16, 1
	v_add3_u32 v192, v192, v160, s39
	global_store_short_d16_hi v141, v192, s[4:5] offset:384
	v_mul_f32_e32 v150, v35, v161
	v_fma_f32 v193, -v209, v150, v193
	v_bfe_u32 v150, v193, 16, 1
	v_add3_u32 v193, v193, v150, s39
	global_store_short_d16_hi v141, v193, s[4:5] offset:2432
	v_mul_f32_e32 v158, v16, v142
	v_fma_f32 v194, -v209, v158, v194
	v_bfe_u32 v158, v194, 16, 1
	v_add3_u32 v194, v194, v158, s39
	global_store_short_d16_hi v140, v194, s[4:5] offset:448
	v_mul_f32_e32 v159, v17, v145
	v_fma_f32 v195, -v209, v159, v195
	v_bfe_u32 v159, v195, 16, 1
	v_add3_u32 v195, v195, v159, s39
	global_store_short_d16_hi v140, v195, s[4:5] offset:2496
	v_mul_f32_e32 v160, v18, v152
	v_fma_f32 v196, -v209, v160, v196
	v_bfe_u32 v160, v196, 16, 1
	v_add3_u32 v196, v196, v160, s39
	global_store_short_d16_hi v141, v196, s[4:5] offset:448
	v_mul_f32_e32 v150, v19, v161
	v_fma_f32 v197, -v209, v150, v197
	v_bfe_u32 v150, v197, 16, 1
	v_add3_u32 v197, v197, v150, s39
	global_store_short_d16_hi v141, v197, s[4:5] offset:2496
	global_load_dwordx4 v[166:169], v128, s[96:97]
	s_add_u32 s96, s96, 0x1000
	s_addc_u32 s97, s97, 0
	global_load_dwordx4 v[170:173], v128, s[96:97]
	s_add_u32 s96, s96, 0x1000
	s_addc_u32 s97, s97, 0
	global_load_dwordx4 v[174:177], v128, s[96:97]
	s_add_u32 s96, s96, 0x1000
	s_addc_u32 s97, s97, 0
	global_load_dwordx4 v[178:181], v128, s[96:97]
	s_add_u32 s96, s96, 0x1000
	s_addc_u32 s97, s97, 0
	global_load_dwordx4 v[182:185], v128, s[96:97]
	s_add_u32 s96, s96, 0x1000
	s_addc_u32 s97, s97, 0
	global_load_dwordx4 v[186:189], v128, s[96:97]
	s_add_u32 s96, s96, 0x1000
	s_addc_u32 s97, s97, 0
	global_load_dwordx4 v[190:193], v128, s[96:97]
	s_add_u32 s96, s96, 0x1000
	s_addc_u32 s97, s97, 0
	global_load_dwordx4 v[194:197], v128, s[96:97]
	s_add_u32 s96, s96, 0x1000
	s_addc_u32 s97, s97, 0
	v_add_u32_e32 v140, 0x4000, v140
	s_waitcnt vmcnt(40)
	v_add_u32_e32 v141, 0x1000, v140
	v_mul_f32_e32 v158, v4, v162
	v_fma_f32 v198, -v209, v158, v198
	v_bfe_u32 v158, v198, 16, 1
	v_add3_u32 v198, v198, v158, s39
	global_store_short_d16_hi v140, v198, s[4:5]
	v_mul_f32_e32 v159, v5, v163
	v_fma_f32 v199, -v209, v159, v199
	v_bfe_u32 v159, v199, 16, 1
	v_add3_u32 v199, v199, v159, s39
	global_store_short_d16_hi v140, v199, s[4:5] offset:2048
	v_mul_f32_e32 v160, v6, v164
	v_fma_f32 v200, -v209, v160, v200
	v_bfe_u32 v160, v200, 16, 1
	v_add3_u32 v200, v200, v160, s39
	global_store_short_d16_hi v141, v200, s[4:5]
	v_mul_f32_e32 v150, v7, v165
	v_fma_f32 v201, -v209, v150, v201
	v_bfe_u32 v150, v201, 16, 1
	v_add3_u32 v201, v201, v150, s39
	global_store_short_d16_hi v141, v201, s[4:5] offset:2048
	v_mul_f32_e32 v158, v116, v162
	v_fma_f32 v202, -v209, v158, v202
	v_bfe_u32 v158, v202, 16, 1
	v_add3_u32 v202, v202, v158, s39
	global_store_short_d16_hi v140, v202, s[4:5] offset:64
	v_mul_f32_e32 v159, v117, v163
	v_fma_f32 v203, -v209, v159, v203
	v_bfe_u32 v159, v203, 16, 1
	v_add3_u32 v203, v203, v159, s39
	global_store_short_d16_hi v140, v203, s[4:5] offset:2112
	v_mul_f32_e32 v160, v118, v164
	v_fma_f32 v204, -v209, v160, v204
	v_bfe_u32 v160, v204, 16, 1
	v_add3_u32 v204, v204, v160, s39
	global_store_short_d16_hi v141, v204, s[4:5] offset:64
	v_mul_f32_e32 v150, v119, v165
	v_fma_f32 v205, -v209, v150, v205
	v_bfe_u32 v150, v205, 16, 1
	v_add3_u32 v205, v205, v150, s39
	global_store_short_d16_hi v141, v205, s[4:5] offset:2112
	v_mul_f32_e32 v158, v100, v162
	v_fma_f32 v240, -v209, v158, v240
	v_bfe_u32 v158, v240, 16, 1
	v_add3_u32 v240, v240, v158, s39
	global_store_short_d16_hi v140, v240, s[4:5] offset:128
	v_mul_f32_e32 v159, v101, v163
	v_fma_f32 v241, -v209, v159, v241
	v_bfe_u32 v159, v241, 16, 1
	v_add3_u32 v241, v241, v159, s39
	global_store_short_d16_hi v140, v241, s[4:5] offset:2176
	v_mul_f32_e32 v160, v102, v164
	v_fma_f32 v242, -v209, v160, v242
	v_bfe_u32 v160, v242, 16, 1
	v_add3_u32 v242, v242, v160, s39
	global_store_short_d16_hi v141, v242, s[4:5] offset:128
	v_mul_f32_e32 v150, v103, v165
	v_fma_f32 v243, -v209, v150, v243
	v_bfe_u32 v150, v243, 16, 1
	v_add3_u32 v243, v243, v150, s39
	global_store_short_d16_hi v141, v243, s[4:5] offset:2176
	v_mul_f32_e32 v158, v84, v162
	v_fma_f32 v244, -v209, v158, v244
	v_bfe_u32 v158, v244, 16, 1
	v_add3_u32 v244, v244, v158, s39
	global_store_short_d16_hi v140, v244, s[4:5] offset:192
	v_mul_f32_e32 v159, v85, v163
	v_fma_f32 v245, -v209, v159, v245
	v_bfe_u32 v159, v245, 16, 1
	v_add3_u32 v245, v245, v159, s39
	global_store_short_d16_hi v140, v245, s[4:5] offset:2240
	v_mul_f32_e32 v160, v86, v164
	v_fma_f32 v246, -v209, v160, v246
	v_bfe_u32 v160, v246, 16, 1
	v_add3_u32 v246, v246, v160, s39
	global_store_short_d16_hi v141, v246, s[4:5] offset:192
	v_mul_f32_e32 v150, v87, v165
	v_fma_f32 v247, -v209, v150, v247
	v_bfe_u32 v150, v247, 16, 1
	v_add3_u32 v247, v247, v150, s39
	global_store_short_d16_hi v141, v247, s[4:5] offset:2240
	v_mul_f32_e32 v158, v68, v162
	v_fma_f32 v248, -v209, v158, v248
	v_bfe_u32 v158, v248, 16, 1
	v_add3_u32 v248, v248, v158, s39
	global_store_short_d16_hi v140, v248, s[4:5] offset:256
	v_mul_f32_e32 v159, v69, v163
	v_fma_f32 v249, -v209, v159, v249
	v_bfe_u32 v159, v249, 16, 1
	v_add3_u32 v249, v249, v159, s39
	global_store_short_d16_hi v140, v249, s[4:5] offset:2304
	v_mul_f32_e32 v160, v70, v164
	v_fma_f32 v250, -v209, v160, v250
	v_bfe_u32 v160, v250, 16, 1
	v_add3_u32 v250, v250, v160, s39
	global_store_short_d16_hi v141, v250, s[4:5] offset:256
	v_mul_f32_e32 v150, v71, v165
	v_fma_f32 v251, -v209, v150, v251
	v_bfe_u32 v150, v251, 16, 1
	v_add3_u32 v251, v251, v150, s39
	global_store_short_d16_hi v141, v251, s[4:5] offset:2304
	v_mul_f32_e32 v158, v52, v162
	v_fma_f32 v252, -v209, v158, v252
	v_bfe_u32 v158, v252, 16, 1
	v_add3_u32 v252, v252, v158, s39
	global_store_short_d16_hi v140, v252, s[4:5] offset:320
	v_mul_f32_e32 v159, v53, v163
	v_fma_f32 v253, -v209, v159, v253
	v_bfe_u32 v159, v253, 16, 1
	v_add3_u32 v253, v253, v159, s39
	global_store_short_d16_hi v140, v253, s[4:5] offset:2368
	v_mul_f32_e32 v160, v54, v164
	v_fma_f32 v254, -v209, v160, v254
	v_bfe_u32 v160, v254, 16, 1
	v_add3_u32 v254, v254, v160, s39
	global_store_short_d16_hi v141, v254, s[4:5] offset:320
	v_mul_f32_e32 v150, v55, v165
	v_fma_f32 v255, -v209, v150, v255
	v_bfe_u32 v150, v255, 16, 1
	v_add3_u32 v255, v255, v150, s39
	global_store_short_d16_hi v141, v255, s[4:5] offset:2368
	v_mul_f32_e32 v158, v36, v162
	v_fma_f32 v232, -v209, v158, v232
	v_bfe_u32 v158, v232, 16, 1
	v_add3_u32 v232, v232, v158, s39
	global_store_short_d16_hi v140, v232, s[4:5] offset:384
	v_mul_f32_e32 v159, v37, v163
	v_fma_f32 v233, -v209, v159, v233
	v_bfe_u32 v159, v233, 16, 1
	v_add3_u32 v233, v233, v159, s39
	global_store_short_d16_hi v140, v233, s[4:5] offset:2432
	v_mul_f32_e32 v160, v38, v164
	v_fma_f32 v234, -v209, v160, v234
	v_bfe_u32 v160, v234, 16, 1
	v_add3_u32 v234, v234, v160, s39
	global_store_short_d16_hi v141, v234, s[4:5] offset:384
	v_mul_f32_e32 v150, v39, v165
	v_fma_f32 v235, -v209, v150, v235
	v_bfe_u32 v150, v235, 16, 1
	v_add3_u32 v235, v235, v150, s39
	global_store_short_d16_hi v141, v235, s[4:5] offset:2432
	v_mul_f32_e32 v158, v20, v162
	v_fma_f32 v154, -v209, v158, v154
	v_bfe_u32 v158, v154, 16, 1
	v_add3_u32 v154, v154, v158, s39
	global_store_short_d16_hi v140, v154, s[4:5] offset:448
	v_mul_f32_e32 v159, v21, v163
	v_fma_f32 v155, -v209, v159, v155
	v_bfe_u32 v159, v155, 16, 1
	v_add3_u32 v155, v155, v159, s39
	global_store_short_d16_hi v140, v155, s[4:5] offset:2496
	v_mul_f32_e32 v160, v22, v164
	v_fma_f32 v156, -v209, v160, v156
	v_bfe_u32 v160, v156, 16, 1
	v_add3_u32 v156, v156, v160, s39
	global_store_short_d16_hi v141, v156, s[4:5] offset:448
	v_mul_f32_e32 v150, v23, v165
	v_fma_f32 v157, -v209, v150, v157
	v_bfe_u32 v150, v157, 16, 1
	v_add3_u32 v157, v157, v150, s39
	global_store_short_d16_hi v141, v157, s[4:5] offset:2496
	global_load_dwordx4 v[198:201], v128, s[96:97]
	s_add_u32 s96, s96, 0x1000
	s_addc_u32 s97, s97, 0
	global_load_dwordx4 v[202:205], v128, s[96:97]
	s_add_u32 s96, s96, 0x1000
	s_addc_u32 s97, s97, 0
	global_load_dwordx4 v[240:243], v128, s[96:97]
	s_add_u32 s96, s96, 0x1000
	s_addc_u32 s97, s97, 0
	global_load_dwordx4 v[244:247], v128, s[96:97]
	s_add_u32 s96, s96, 0x1000
	s_addc_u32 s97, s97, 0
	global_load_dwordx4 v[248:251], v128, s[96:97]
	s_add_u32 s96, s96, 0x1000
	s_addc_u32 s97, s97, 0
	global_load_dwordx4 v[252:255], v128, s[96:97]
	s_add_u32 s96, s96, 0x1000
	s_addc_u32 s97, s97, 0
	global_load_dwordx4 v[232:235], v128, s[96:97]
	s_add_u32 s96, s96, 0x1000
	s_addc_u32 s97, s97, 0
	global_load_dwordx4 v[154:157], v128, s[96:97]
	s_add_u32 s96, s96, 0x1000
	s_addc_u32 s97, s97, 0
	v_add_u32_e32 v140, 0x4000, v140
	s_waitcnt vmcnt(40)
	v_add_u32_e32 v141, 0x1000, v140
	v_mul_f32_e32 v158, v8, v137
	v_fma_f32 v166, -v209, v158, v166
	v_bfe_u32 v158, v166, 16, 1
	v_add3_u32 v166, v166, v158, s39
	global_store_short_d16_hi v140, v166, s[4:5]
	v_mul_f32_e32 v159, v9, v136
	v_fma_f32 v167, -v209, v159, v167
	v_bfe_u32 v159, v167, 16, 1
	v_add3_u32 v167, v167, v159, s39
	global_store_short_d16_hi v140, v167, s[4:5] offset:2048
	v_mul_f32_e32 v160, v10, v135
	v_fma_f32 v168, -v209, v160, v168
	v_bfe_u32 v160, v168, 16, 1
	v_add3_u32 v168, v168, v160, s39
	global_store_short_d16_hi v141, v168, s[4:5]
	v_mul_f32_e32 v150, v11, v134
	v_fma_f32 v169, -v209, v150, v169
	v_bfe_u32 v150, v169, 16, 1
	v_add3_u32 v169, v169, v150, s39
	global_store_short_d16_hi v141, v169, s[4:5] offset:2048
	v_mul_f32_e32 v158, v120, v137
	v_fma_f32 v170, -v209, v158, v170
	v_bfe_u32 v158, v170, 16, 1
	v_add3_u32 v170, v170, v158, s39
	global_store_short_d16_hi v140, v170, s[4:5] offset:64
	v_mul_f32_e32 v159, v121, v136
	v_fma_f32 v171, -v209, v159, v171
	v_bfe_u32 v159, v171, 16, 1
	v_add3_u32 v171, v171, v159, s39
	global_store_short_d16_hi v140, v171, s[4:5] offset:2112
	v_mul_f32_e32 v160, v122, v135
	v_fma_f32 v172, -v209, v160, v172
	v_bfe_u32 v160, v172, 16, 1
	v_add3_u32 v172, v172, v160, s39
	global_store_short_d16_hi v141, v172, s[4:5] offset:64
	v_mul_f32_e32 v150, v123, v134
	v_fma_f32 v173, -v209, v150, v173
	v_bfe_u32 v150, v173, 16, 1
	v_add3_u32 v173, v173, v150, s39
	global_store_short_d16_hi v141, v173, s[4:5] offset:2112
	v_mul_f32_e32 v158, v104, v137
	v_fma_f32 v174, -v209, v158, v174
	v_bfe_u32 v158, v174, 16, 1
	v_add3_u32 v174, v174, v158, s39
	global_store_short_d16_hi v140, v174, s[4:5] offset:128
	v_mul_f32_e32 v159, v105, v136
	v_fma_f32 v175, -v209, v159, v175
	v_bfe_u32 v159, v175, 16, 1
	v_add3_u32 v175, v175, v159, s39
	global_store_short_d16_hi v140, v175, s[4:5] offset:2176
	v_mul_f32_e32 v160, v106, v135
	v_fma_f32 v176, -v209, v160, v176
	v_bfe_u32 v160, v176, 16, 1
	v_add3_u32 v176, v176, v160, s39
	global_store_short_d16_hi v141, v176, s[4:5] offset:128
	v_mul_f32_e32 v150, v107, v134
	v_fma_f32 v177, -v209, v150, v177
	v_bfe_u32 v150, v177, 16, 1
	v_add3_u32 v177, v177, v150, s39
	global_store_short_d16_hi v141, v177, s[4:5] offset:2176
	v_mul_f32_e32 v158, v88, v137
	v_fma_f32 v178, -v209, v158, v178
	v_bfe_u32 v158, v178, 16, 1
	v_add3_u32 v178, v178, v158, s39
	global_store_short_d16_hi v140, v178, s[4:5] offset:192
	v_mul_f32_e32 v159, v89, v136
	v_fma_f32 v179, -v209, v159, v179
	v_bfe_u32 v159, v179, 16, 1
	v_add3_u32 v179, v179, v159, s39
	global_store_short_d16_hi v140, v179, s[4:5] offset:2240
	v_mul_f32_e32 v160, v90, v135
	v_fma_f32 v180, -v209, v160, v180
	v_bfe_u32 v160, v180, 16, 1
	v_add3_u32 v180, v180, v160, s39
	global_store_short_d16_hi v141, v180, s[4:5] offset:192
	v_mul_f32_e32 v150, v91, v134
	v_fma_f32 v181, -v209, v150, v181
	v_bfe_u32 v150, v181, 16, 1
	v_add3_u32 v181, v181, v150, s39
	global_store_short_d16_hi v141, v181, s[4:5] offset:2240
	v_mul_f32_e32 v158, v72, v137
	v_fma_f32 v182, -v209, v158, v182
	v_bfe_u32 v158, v182, 16, 1
	v_add3_u32 v182, v182, v158, s39
	global_store_short_d16_hi v140, v182, s[4:5] offset:256
	v_mul_f32_e32 v159, v73, v136
	v_fma_f32 v183, -v209, v159, v183
	v_bfe_u32 v159, v183, 16, 1
	v_add3_u32 v183, v183, v159, s39
	global_store_short_d16_hi v140, v183, s[4:5] offset:2304
	v_mul_f32_e32 v160, v74, v135
	v_fma_f32 v184, -v209, v160, v184
	v_bfe_u32 v160, v184, 16, 1
	v_add3_u32 v184, v184, v160, s39
	global_store_short_d16_hi v141, v184, s[4:5] offset:256
	v_mul_f32_e32 v150, v75, v134
	v_fma_f32 v185, -v209, v150, v185
	v_bfe_u32 v150, v185, 16, 1
	v_add3_u32 v185, v185, v150, s39
	global_store_short_d16_hi v141, v185, s[4:5] offset:2304
	v_mul_f32_e32 v158, v56, v137
	v_fma_f32 v186, -v209, v158, v186
	v_bfe_u32 v158, v186, 16, 1
	v_add3_u32 v186, v186, v158, s39
	global_store_short_d16_hi v140, v186, s[4:5] offset:320
	v_mul_f32_e32 v159, v57, v136
	v_fma_f32 v187, -v209, v159, v187
	v_bfe_u32 v159, v187, 16, 1
	v_add3_u32 v187, v187, v159, s39
	global_store_short_d16_hi v140, v187, s[4:5] offset:2368
	v_mul_f32_e32 v160, v58, v135
	v_fma_f32 v188, -v209, v160, v188
	v_bfe_u32 v160, v188, 16, 1
	v_add3_u32 v188, v188, v160, s39
	global_store_short_d16_hi v141, v188, s[4:5] offset:320
	v_mul_f32_e32 v150, v59, v134
	v_fma_f32 v189, -v209, v150, v189
	v_bfe_u32 v150, v189, 16, 1
	v_add3_u32 v189, v189, v150, s39
	global_store_short_d16_hi v141, v189, s[4:5] offset:2368
	v_mul_f32_e32 v158, v40, v137
	v_fma_f32 v190, -v209, v158, v190
	v_bfe_u32 v158, v190, 16, 1
	v_add3_u32 v190, v190, v158, s39
	global_store_short_d16_hi v140, v190, s[4:5] offset:384
	v_mul_f32_e32 v159, v41, v136
	v_fma_f32 v191, -v209, v159, v191
	v_bfe_u32 v159, v191, 16, 1
	v_add3_u32 v191, v191, v159, s39
	global_store_short_d16_hi v140, v191, s[4:5] offset:2432
	v_mul_f32_e32 v160, v42, v135
	v_fma_f32 v192, -v209, v160, v192
	v_bfe_u32 v160, v192, 16, 1
	v_add3_u32 v192, v192, v160, s39
	global_store_short_d16_hi v141, v192, s[4:5] offset:384
	v_mul_f32_e32 v150, v43, v134
	v_fma_f32 v193, -v209, v150, v193
	v_bfe_u32 v150, v193, 16, 1
	v_add3_u32 v193, v193, v150, s39
	global_store_short_d16_hi v141, v193, s[4:5] offset:2432
	v_mul_f32_e32 v158, v24, v137
	v_fma_f32 v194, -v209, v158, v194
	v_bfe_u32 v158, v194, 16, 1
	v_add3_u32 v194, v194, v158, s39
	global_store_short_d16_hi v140, v194, s[4:5] offset:448
	v_mul_f32_e32 v159, v25, v136
	v_fma_f32 v195, -v209, v159, v195
	v_bfe_u32 v159, v195, 16, 1
	v_add3_u32 v195, v195, v159, s39
	global_store_short_d16_hi v140, v195, s[4:5] offset:2496
	v_mul_f32_e32 v160, v26, v135
	v_fma_f32 v196, -v209, v160, v196
	v_bfe_u32 v160, v196, 16, 1
	v_add3_u32 v196, v196, v160, s39
	global_store_short_d16_hi v141, v196, s[4:5] offset:448
	v_mul_f32_e32 v150, v27, v134
	v_fma_f32 v197, -v209, v150, v197
	v_bfe_u32 v150, v197, 16, 1
	v_add3_u32 v197, v197, v150, s39
	global_store_short_d16_hi v141, v197, s[4:5] offset:2496
	v_add_u32_e32 v140, 0x4000, v140
	s_waitcnt vmcnt(32)
	v_add_u32_e32 v141, 0x1000, v140
	v_mul_f32_e32 v158, v12, v133
	v_fma_f32 v198, -v209, v158, v198
	v_bfe_u32 v158, v198, 16, 1
	v_add3_u32 v198, v198, v158, s39
	global_store_short_d16_hi v140, v198, s[4:5]
	v_mul_f32_e32 v159, v13, v132
	v_fma_f32 v199, -v209, v159, v199
	v_bfe_u32 v159, v199, 16, 1
	v_add3_u32 v199, v199, v159, s39
	global_store_short_d16_hi v140, v199, s[4:5] offset:2048
	v_mul_f32_e32 v160, v14, v131
	v_fma_f32 v200, -v209, v160, v200
	v_bfe_u32 v160, v200, 16, 1
	v_add3_u32 v200, v200, v160, s39
	global_store_short_d16_hi v141, v200, s[4:5]
	v_mul_f32_e32 v150, v15, v130
	v_fma_f32 v201, -v209, v150, v201
	v_bfe_u32 v150, v201, 16, 1
	v_add3_u32 v201, v201, v150, s39
	global_store_short_d16_hi v141, v201, s[4:5] offset:2048
	v_mul_f32_e32 v158, v124, v133
	v_fma_f32 v202, -v209, v158, v202
	v_bfe_u32 v158, v202, 16, 1
	v_add3_u32 v202, v202, v158, s39
	global_store_short_d16_hi v140, v202, s[4:5] offset:64
	v_mul_f32_e32 v159, v125, v132
	v_fma_f32 v203, -v209, v159, v203
	v_bfe_u32 v159, v203, 16, 1
	v_add3_u32 v203, v203, v159, s39
	global_store_short_d16_hi v140, v203, s[4:5] offset:2112
	v_mul_f32_e32 v160, v126, v131
	v_fma_f32 v204, -v209, v160, v204
	v_bfe_u32 v160, v204, 16, 1
	v_add3_u32 v204, v204, v160, s39
	global_store_short_d16_hi v141, v204, s[4:5] offset:64
	v_mul_f32_e32 v150, v127, v130
	v_fma_f32 v205, -v209, v150, v205
	v_bfe_u32 v150, v205, 16, 1
	v_add3_u32 v205, v205, v150, s39
	global_store_short_d16_hi v141, v205, s[4:5] offset:2112
	v_mul_f32_e32 v158, v108, v133
	v_fma_f32 v240, -v209, v158, v240
	v_bfe_u32 v158, v240, 16, 1
	v_add3_u32 v240, v240, v158, s39
	global_store_short_d16_hi v140, v240, s[4:5] offset:128
	v_mul_f32_e32 v159, v109, v132
	v_fma_f32 v241, -v209, v159, v241
	v_bfe_u32 v159, v241, 16, 1
	v_add3_u32 v241, v241, v159, s39
	global_store_short_d16_hi v140, v241, s[4:5] offset:2176
	v_mul_f32_e32 v160, v110, v131
	v_fma_f32 v242, -v209, v160, v242
	v_bfe_u32 v160, v242, 16, 1
	v_add3_u32 v242, v242, v160, s39
	global_store_short_d16_hi v141, v242, s[4:5] offset:128
	v_mul_f32_e32 v150, v111, v130
	v_fma_f32 v243, -v209, v150, v243
	v_bfe_u32 v150, v243, 16, 1
	v_add3_u32 v243, v243, v150, s39
	global_store_short_d16_hi v141, v243, s[4:5] offset:2176
	v_mul_f32_e32 v158, v92, v133
	v_fma_f32 v244, -v209, v158, v244
	v_bfe_u32 v158, v244, 16, 1
	v_add3_u32 v244, v244, v158, s39
	global_store_short_d16_hi v140, v244, s[4:5] offset:192
	v_mul_f32_e32 v159, v93, v132
	v_fma_f32 v245, -v209, v159, v245
	v_bfe_u32 v159, v245, 16, 1
	v_add3_u32 v245, v245, v159, s39
	global_store_short_d16_hi v140, v245, s[4:5] offset:2240
	v_mul_f32_e32 v160, v94, v131
	v_fma_f32 v246, -v209, v160, v246
	v_bfe_u32 v160, v246, 16, 1
	v_add3_u32 v246, v246, v160, s39
	global_store_short_d16_hi v141, v246, s[4:5] offset:192
	v_mul_f32_e32 v150, v95, v130
	v_fma_f32 v247, -v209, v150, v247
	v_bfe_u32 v150, v247, 16, 1
	v_add3_u32 v247, v247, v150, s39
	global_store_short_d16_hi v141, v247, s[4:5] offset:2240
	v_mul_f32_e32 v158, v76, v133
	v_fma_f32 v248, -v209, v158, v248
	v_bfe_u32 v158, v248, 16, 1
	v_add3_u32 v248, v248, v158, s39
	global_store_short_d16_hi v140, v248, s[4:5] offset:256
	v_mul_f32_e32 v159, v77, v132
	v_fma_f32 v249, -v209, v159, v249
	v_bfe_u32 v159, v249, 16, 1
	v_add3_u32 v249, v249, v159, s39
	global_store_short_d16_hi v140, v249, s[4:5] offset:2304
	v_mul_f32_e32 v160, v78, v131
	v_fma_f32 v250, -v209, v160, v250
	v_bfe_u32 v160, v250, 16, 1
	v_add3_u32 v250, v250, v160, s39
	global_store_short_d16_hi v141, v250, s[4:5] offset:256
	v_mul_f32_e32 v150, v79, v130
	v_fma_f32 v251, -v209, v150, v251
	v_bfe_u32 v150, v251, 16, 1
	v_add3_u32 v251, v251, v150, s39
	global_store_short_d16_hi v141, v251, s[4:5] offset:2304
	v_mul_f32_e32 v158, v60, v133
	v_fma_f32 v252, -v209, v158, v252
	v_bfe_u32 v158, v252, 16, 1
	v_add3_u32 v252, v252, v158, s39
	global_store_short_d16_hi v140, v252, s[4:5] offset:320
	v_mul_f32_e32 v159, v61, v132
	v_fma_f32 v253, -v209, v159, v253
	v_bfe_u32 v159, v253, 16, 1
	v_add3_u32 v253, v253, v159, s39
	global_store_short_d16_hi v140, v253, s[4:5] offset:2368
	v_mul_f32_e32 v160, v62, v131
	v_fma_f32 v254, -v209, v160, v254
	v_bfe_u32 v160, v254, 16, 1
	v_add3_u32 v254, v254, v160, s39
	global_store_short_d16_hi v141, v254, s[4:5] offset:320
	v_mul_f32_e32 v150, v63, v130
	v_fma_f32 v255, -v209, v150, v255
	v_bfe_u32 v150, v255, 16, 1
	v_add3_u32 v255, v255, v150, s39
	global_store_short_d16_hi v141, v255, s[4:5] offset:2368
	v_mul_f32_e32 v158, v44, v133
	v_fma_f32 v232, -v209, v158, v232
	v_bfe_u32 v158, v232, 16, 1
	v_add3_u32 v232, v232, v158, s39
	global_store_short_d16_hi v140, v232, s[4:5] offset:384
	v_mul_f32_e32 v159, v45, v132
	v_fma_f32 v233, -v209, v159, v233
	v_bfe_u32 v159, v233, 16, 1
	v_add3_u32 v233, v233, v159, s39
	global_store_short_d16_hi v140, v233, s[4:5] offset:2432
	v_mul_f32_e32 v160, v46, v131
	v_fma_f32 v234, -v209, v160, v234
	v_bfe_u32 v160, v234, 16, 1
	v_add3_u32 v234, v234, v160, s39
	global_store_short_d16_hi v141, v234, s[4:5] offset:384
	v_mul_f32_e32 v150, v47, v130
	v_fma_f32 v235, -v209, v150, v235
	v_bfe_u32 v150, v235, 16, 1
	v_add3_u32 v235, v235, v150, s39
	global_store_short_d16_hi v141, v235, s[4:5] offset:2432
	v_mul_f32_e32 v158, v28, v133
	v_fma_f32 v154, -v209, v158, v154
	v_bfe_u32 v158, v154, 16, 1
	v_add3_u32 v154, v154, v158, s39
	global_store_short_d16_hi v140, v154, s[4:5] offset:448
	v_mul_f32_e32 v159, v29, v132
	v_fma_f32 v155, -v209, v159, v155
	v_bfe_u32 v159, v155, 16, 1
	v_add3_u32 v155, v155, v159, s39
	global_store_short_d16_hi v140, v155, s[4:5] offset:2496
	v_mul_f32_e32 v160, v30, v131
	v_fma_f32 v156, -v209, v160, v156
	v_bfe_u32 v160, v156, 16, 1
	v_add3_u32 v156, v156, v160, s39
	global_store_short_d16_hi v141, v156, s[4:5] offset:448
	v_mul_f32_e32 v150, v31, v130
	v_fma_f32 v157, -v209, v150, v157
	v_bfe_u32 v150, v157, 16, 1
	v_add3_u32 v157, v157, v150, s39
	global_store_short_d16_hi v141, v157, s[4:5] offset:2496
	s_branch .LBB0_508

.LBB0_914:
	v_mov_b32_e32 v129, v144
	s_nop 1
	v_permlane32_swap_b32_e32 v144, v129
	v_add_f32_e32 v144, v144, v129
	s_and_saveexec_b64 s[4:5], s[0:1]
	ds_write_b32 v224, v144
	s_or_b64 exec, exec, s[4:5]
	s_waitcnt lgkmcnt(0)
	v_add_u32_e32 v136, s21, v210
	ds_read_b128 v[128:131], v136
	ds_read_b128 v[132:135], v136 offset:32
	s_ashr_i32 s21, s20, 31
	s_lshl_b64 s[0:1], s[20:21], 12
	ds_read_b128 v[138:141], v136 offset:96
	s_waitcnt lgkmcnt(2)
	v_rcp_f32_e32 v142, v128
	v_rcp_f32_e32 v145, v129
	v_rcp_f32_e32 v152, v130
	v_rcp_f32_e32 v161, v131
	ds_read_b128 v[128:131], v136 offset:64
	s_waitcnt lgkmcnt(2)
	v_rcp_f32_e32 v162, v132
	v_rcp_f32_e32 v163, v133
	v_rcp_f32_e32 v164, v134
	v_rcp_f32_e32 v165, v135
	s_waitcnt lgkmcnt(0)
	v_rcp_f32_e32 v137, v128
	v_rcp_f32_e32 v136, v129
	v_rcp_f32_e32 v135, v130
	v_rcp_f32_e32 v134, v131
	v_rcp_f32_e32 v133, v138
	v_rcp_f32_e32 v132, v139
	v_rcp_f32_e32 v131, v140
	v_rcp_f32_e32 v130, v141
	s_add_u32 s0, s66, s0
	s_addc_u32 s1, s67, s1
	s_mov_b64 s[4:5], -1
	s_andn2_b64 vcc, exec, s[18:19]
	v_lshlrev_b32_e32 v210, 2, v219
	v_lshlrev_b32_e32 v128, 14, v218
	v_lshl_add_u32 v129, v218, 5, v219
	v_lshlrev_b32_e32 v128, 4, v129
	s_mov_b32 s96, s0
	s_mov_b32 s97, s1
	s_cbranch_vccnz .Lepi1_p0
	s_lshl_b64 s[4:5], s[20:21], 11
	s_add_u32 s4, s68, s4
	s_addc_u32 s5, s69, s5
	v_lshlrev_b32_e32 v140, 1, v219
	v_lshl_add_u32 v140, v218, 13, v140
	v_mov_b32_e32 v141, 0
	s_nop 0
	s_mov_b64 s[100:101], 0x1000
	s_mov_b64 s[98:99], 0x4000
	global_load_dwordx4 v[166:169], v128, s[96:97]
	s_add_u32 s96, s96, 0x1000
	s_addc_u32 s97, s97, 0
	global_load_dwordx4 v[170:173], v128, s[96:97]
	s_add_u32 s96, s96, 0x1000
	s_addc_u32 s97, s97, 0
	global_load_dwordx4 v[174:177], v128, s[96:97]
	s_add_u32 s96, s96, 0x1000
	s_addc_u32 s97, s97, 0
	global_load_dwordx4 v[178:181], v128, s[96:97]
	s_add_u32 s96, s96, 0x1000
	s_addc_u32 s97, s97, 0
	global_load_dwordx4 v[182:185], v128, s[96:97]
	s_add_u32 s96, s96, 0x1000
	s_addc_u32 s97, s97, 0
	global_load_dwordx4 v[186:189], v128, s[96:97]
	s_add_u32 s96, s96, 0x1000
	s_addc_u32 s97, s97, 0
	global_load_dwordx4 v[190:193], v128, s[96:97]
	s_add_u32 s96, s96, 0x1000
	s_addc_u32 s97, s97, 0
	global_load_dwordx4 v[194:197], v128, s[96:97]
	s_add_u32 s96, s96, 0x1000
	s_addc_u32 s97, s97, 0
	global_load_dwordx4 v[198:201], v128, s[96:97]
	s_add_u32 s96, s96, 0x1000
	s_addc_u32 s97, s97, 0
	global_load_dwordx4 v[202:205], v128, s[96:97]
	s_add_u32 s96, s96, 0x1000
	s_addc_u32 s97, s97, 0
	global_load_dwordx4 v[240:243], v128, s[96:97]
	s_add_u32 s96, s96, 0x1000
	s_addc_u32 s97, s97, 0
	global_load_dwordx4 v[244:247], v128, s[96:97]
	s_add_u32 s96, s96, 0x1000
	s_addc_u32 s97, s97, 0
	global_load_dwordx4 v[248:251], v128, s[96:97]
	s_add_u32 s96, s96, 0x1000
	s_addc_u32 s97, s97, 0
	global_load_dwordx4 v[252:255], v128, s[96:97]
	s_add_u32 s96, s96, 0x1000
	s_addc_u32 s97, s97, 0
	global_load_dwordx4 v[232:235], v128, s[96:97]
	s_add_u32 s96, s96, 0x1000
	s_addc_u32 s97, s97, 0
	global_load_dwordx4 v[154:157], v128, s[96:97]
	s_add_u32 s96, s96, 0x1000
	s_addc_u32 s97, s97, 0
	s_waitcnt vmcnt(8)
	v_add_u32_e32 v141, 0x1000, v140
	v_mul_f32_e32 v158, v0, v142
	v_fma_f32 v166, -v209, v158, v166
	v_bfe_u32 v158, v166, 16, 1
	v_add3_u32 v166, v166, v158, s43
	global_store_short_d16_hi v140, v166, s[4:5]
	v_mul_f32_e32 v159, v1, v145
	v_fma_f32 v167, -v209, v159, v167
	v_bfe_u32 v159, v167, 16, 1
	v_add3_u32 v167, v167, v159, s43
	global_store_short_d16_hi v140, v167, s[4:5] offset:2048
	v_mul_f32_e32 v160, v2, v152
	v_fma_f32 v168, -v209, v160, v168
	v_bfe_u32 v160, v168, 16, 1
	v_add3_u32 v168, v168, v160, s43
	global_store_short_d16_hi v141, v168, s[4:5]
	v_mul_f32_e32 v150, v3, v161
	v_fma_f32 v169, -v209, v150, v169
	v_bfe_u32 v150, v169, 16, 1
	v_add3_u32 v169, v169, v150, s43
	global_store_short_d16_hi v141, v169, s[4:5] offset:2048
	v_mul_f32_e32 v158, v112, v142
	v_fma_f32 v170, -v209, v158, v170
	v_bfe_u32 v158, v170, 16, 1
	v_add3_u32 v170, v170, v158, s43
	global_store_short_d16_hi v140, v170, s[4:5] offset:64
	v_mul_f32_e32 v159, v113, v145
	v_fma_f32 v171, -v209, v159, v171
	v_bfe_u32 v159, v171, 16, 1
	v_add3_u32 v171, v171, v159, s43
	global_store_short_d16_hi v140, v171, s[4:5] offset:2112
	v_mul_f32_e32 v160, v114, v152
	v_fma_f32 v172, -v209, v160, v172
	v_bfe_u32 v160, v172, 16, 1
	v_add3_u32 v172, v172, v160, s43
	global_store_short_d16_hi v141, v172, s[4:5] offset:64
	v_mul_f32_e32 v150, v115, v161
	v_fma_f32 v173, -v209, v150, v173
	v_bfe_u32 v150, v173, 16, 1
	v_add3_u32 v173, v173, v150, s43
	global_store_short_d16_hi v141, v173, s[4:5] offset:2112
	v_mul_f32_e32 v158, v96, v142
	v_fma_f32 v174, -v209, v158, v174
	v_bfe_u32 v158, v174, 16, 1
	v_add3_u32 v174, v174, v158, s43
	global_store_short_d16_hi v140, v174, s[4:5] offset:128
	v_mul_f32_e32 v159, v97, v145
	v_fma_f32 v175, -v209, v159, v175
	v_bfe_u32 v159, v175, 16, 1
	v_add3_u32 v175, v175, v159, s43
	global_store_short_d16_hi v140, v175, s[4:5] offset:2176
	v_mul_f32_e32 v160, v98, v152
	v_fma_f32 v176, -v209, v160, v176
	v_bfe_u32 v160, v176, 16, 1
	v_add3_u32 v176, v176, v160, s43
	global_store_short_d16_hi v141, v176, s[4:5] offset:128
	v_mul_f32_e32 v150, v99, v161
	v_fma_f32 v177, -v209, v150, v177
	v_bfe_u32 v150, v177, 16, 1
	v_add3_u32 v177, v177, v150, s43
	global_store_short_d16_hi v141, v177, s[4:5] offset:2176
	v_mul_f32_e32 v158, v80, v142
	v_fma_f32 v178, -v209, v158, v178
	v_bfe_u32 v158, v178, 16, 1
	v_add3_u32 v178, v178, v158, s43
	global_store_short_d16_hi v140, v178, s[4:5] offset:192
	v_mul_f32_e32 v159, v81, v145
	v_fma_f32 v179, -v209, v159, v179
	v_bfe_u32 v159, v179, 16, 1
	v_add3_u32 v179, v179, v159, s43
	global_store_short_d16_hi v140, v179, s[4:5] offset:2240
	v_mul_f32_e32 v160, v82, v152
	v_fma_f32 v180, -v209, v160, v180
	v_bfe_u32 v160, v180, 16, 1
	v_add3_u32 v180, v180, v160, s43
	global_store_short_d16_hi v141, v180, s[4:5] offset:192
	v_mul_f32_e32 v150, v83, v161
	v_fma_f32 v181, -v209, v150, v181
	v_bfe_u32 v150, v181, 16, 1
	v_add3_u32 v181, v181, v150, s43
	global_store_short_d16_hi v141, v181, s[4:5] offset:2240
	v_mul_f32_e32 v158, v64, v142
	v_fma_f32 v182, -v209, v158, v182
	v_bfe_u32 v158, v182, 16, 1
	v_add3_u32 v182, v182, v158, s43
	global_store_short_d16_hi v140, v182, s[4:5] offset:256
	v_mul_f32_e32 v159, v65, v145
	v_fma_f32 v183, -v209, v159, v183
	v_bfe_u32 v159, v183, 16, 1
	v_add3_u32 v183, v183, v159, s43
	global_store_short_d16_hi v140, v183, s[4:5] offset:2304
	v_mul_f32_e32 v160, v66, v152
	v_fma_f32 v184, -v209, v160, v184
	v_bfe_u32 v160, v184, 16, 1
	v_add3_u32 v184, v184, v160, s43
	global_store_short_d16_hi v141, v184, s[4:5] offset:256
	v_mul_f32_e32 v150, v67, v161
	v_fma_f32 v185, -v209, v150, v185
	v_bfe_u32 v150, v185, 16, 1
	v_add3_u32 v185, v185, v150, s43
	global_store_short_d16_hi v141, v185, s[4:5] offset:2304
	v_mul_f32_e32 v158, v48, v142
	v_fma_f32 v186, -v209, v158, v186
	v_bfe_u32 v158, v186, 16, 1
	v_add3_u32 v186, v186, v158, s43
	global_store_short_d16_hi v140, v186, s[4:5] offset:320
	v_mul_f32_e32 v159, v49, v145
	v_fma_f32 v187, -v209, v159, v187
	v_bfe_u32 v159, v187, 16, 1
	v_add3_u32 v187, v187, v159, s43
	global_store_short_d16_hi v140, v187, s[4:5] offset:2368
	v_mul_f32_e32 v160, v50, v152
	v_fma_f32 v188, -v209, v160, v188
	v_bfe_u32 v160, v188, 16, 1
	v_add3_u32 v188, v188, v160, s43
	global_store_short_d16_hi v141, v188, s[4:5] offset:320
	v_mul_f32_e32 v150, v51, v161
	v_fma_f32 v189, -v209, v150, v189
	v_bfe_u32 v150, v189, 16, 1
	v_add3_u32 v189, v189, v150, s43
	global_store_short_d16_hi v141, v189, s[4:5] offset:2368
	v_mul_f32_e32 v158, v32, v142
	v_fma_f32 v190, -v209, v158, v190
	v_bfe_u32 v158, v190, 16, 1
	v_add3_u32 v190, v190, v158, s43
	global_store_short_d16_hi v140, v190, s[4:5] offset:384
	v_mul_f32_e32 v159, v33, v145
	v_fma_f32 v191, -v209, v159, v191
	v_bfe_u32 v159, v191, 16, 1
	v_add3_u32 v191, v191, v159, s43
	global_store_short_d16_hi v140, v191, s[4:5] offset:2432
	v_mul_f32_e32 v160, v34, v152
	v_fma_f32 v192, -v209, v160, v192
	v_bfe_u32 v160, v192, 16, 1
	v_add3_u32 v192, v192, v160, s43
	global_store_short_d16_hi v141, v192, s[4:5] offset:384
	v_mul_f32_e32 v150, v35, v161
	v_fma_f32 v193, -v209, v150, v193
	v_bfe_u32 v150, v193, 16, 1
	v_add3_u32 v193, v193, v150, s43
	global_store_short_d16_hi v141, v193, s[4:5] offset:2432
	v_mul_f32_e32 v158, v16, v142
	v_fma_f32 v194, -v209, v158, v194
	v_bfe_u32 v158, v194, 16, 1
	v_add3_u32 v194, v194, v158, s43
	global_store_short_d16_hi v140, v194, s[4:5] offset:448
	v_mul_f32_e32 v159, v17, v145
	v_fma_f32 v195, -v209, v159, v195
	v_bfe_u32 v159, v195, 16, 1
	v_add3_u32 v195, v195, v159, s43
	global_store_short_d16_hi v140, v195, s[4:5] offset:2496
	v_mul_f32_e32 v160, v18, v152
	v_fma_f32 v196, -v209, v160, v196
	v_bfe_u32 v160, v196, 16, 1
	v_add3_u32 v196, v196, v160, s43
	global_store_short_d16_hi v141, v196, s[4:5] offset:448
	v_mul_f32_e32 v150, v19, v161
	v_fma_f32 v197, -v209, v150, v197
	v_bfe_u32 v150, v197, 16, 1
	v_add3_u32 v197, v197, v150, s43
	global_store_short_d16_hi v141, v197, s[4:5] offset:2496
	global_load_dwordx4 v[166:169], v128, s[96:97]
	s_add_u32 s96, s96, 0x1000
	s_addc_u32 s97, s97, 0
	global_load_dwordx4 v[170:173], v128, s[96:97]
	s_add_u32 s96, s96, 0x1000
	s_addc_u32 s97, s97, 0
	global_load_dwordx4 v[174:177], v128, s[96:97]
	s_add_u32 s96, s96, 0x1000
	s_addc_u32 s97, s97, 0
	global_load_dwordx4 v[178:181], v128, s[96:97]
	s_add_u32 s96, s96, 0x1000
	s_addc_u32 s97, s97, 0
	global_load_dwordx4 v[182:185], v128, s[96:97]
	s_add_u32 s96, s96, 0x1000
	s_addc_u32 s97, s97, 0
	global_load_dwordx4 v[186:189], v128, s[96:97]
	s_add_u32 s96, s96, 0x1000
	s_addc_u32 s97, s97, 0
	global_load_dwordx4 v[190:193], v128, s[96:97]
	s_add_u32 s96, s96, 0x1000
	s_addc_u32 s97, s97, 0
	global_load_dwordx4 v[194:197], v128, s[96:97]
	s_add_u32 s96, s96, 0x1000
	s_addc_u32 s97, s97, 0
	v_add_u32_e32 v140, 0x4000, v140
	s_waitcnt vmcnt(40)
	v_add_u32_e32 v141, 0x1000, v140
	v_mul_f32_e32 v158, v4, v162
	v_fma_f32 v198, -v209, v158, v198
	v_bfe_u32 v158, v198, 16, 1
	v_add3_u32 v198, v198, v158, s43
	global_store_short_d16_hi v140, v198, s[4:5]
	v_mul_f32_e32 v159, v5, v163
	v_fma_f32 v199, -v209, v159, v199
	v_bfe_u32 v159, v199, 16, 1
	v_add3_u32 v199, v199, v159, s43
	global_store_short_d16_hi v140, v199, s[4:5] offset:2048
	v_mul_f32_e32 v160, v6, v164
	v_fma_f32 v200, -v209, v160, v200
	v_bfe_u32 v160, v200, 16, 1
	v_add3_u32 v200, v200, v160, s43
	global_store_short_d16_hi v141, v200, s[4:5]
	v_mul_f32_e32 v150, v7, v165
	v_fma_f32 v201, -v209, v150, v201
	v_bfe_u32 v150, v201, 16, 1
	v_add3_u32 v201, v201, v150, s43
	global_store_short_d16_hi v141, v201, s[4:5] offset:2048
	v_mul_f32_e32 v158, v116, v162
	v_fma_f32 v202, -v209, v158, v202
	v_bfe_u32 v158, v202, 16, 1
	v_add3_u32 v202, v202, v158, s43
	global_store_short_d16_hi v140, v202, s[4:5] offset:64
	v_mul_f32_e32 v159, v117, v163
	v_fma_f32 v203, -v209, v159, v203
	v_bfe_u32 v159, v203, 16, 1
	v_add3_u32 v203, v203, v159, s43
	global_store_short_d16_hi v140, v203, s[4:5] offset:2112
	v_mul_f32_e32 v160, v118, v164
	v_fma_f32 v204, -v209, v160, v204
	v_bfe_u32 v160, v204, 16, 1
	v_add3_u32 v204, v204, v160, s43
	global_store_short_d16_hi v141, v204, s[4:5] offset:64
	v_mul_f32_e32 v150, v119, v165
	v_fma_f32 v205, -v209, v150, v205
	v_bfe_u32 v150, v205, 16, 1
	v_add3_u32 v205, v205, v150, s43
	global_store_short_d16_hi v141, v205, s[4:5] offset:2112
	v_mul_f32_e32 v158, v100, v162
	v_fma_f32 v240, -v209, v158, v240
	v_bfe_u32 v158, v240, 16, 1
	v_add3_u32 v240, v240, v158, s43
	global_store_short_d16_hi v140, v240, s[4:5] offset:128
	v_mul_f32_e32 v159, v101, v163
	v_fma_f32 v241, -v209, v159, v241
	v_bfe_u32 v159, v241, 16, 1
	v_add3_u32 v241, v241, v159, s43
	global_store_short_d16_hi v140, v241, s[4:5] offset:2176
	v_mul_f32_e32 v160, v102, v164
	v_fma_f32 v242, -v209, v160, v242
	v_bfe_u32 v160, v242, 16, 1
	v_add3_u32 v242, v242, v160, s43
	global_store_short_d16_hi v141, v242, s[4:5] offset:128
	v_mul_f32_e32 v150, v103, v165
	v_fma_f32 v243, -v209, v150, v243
	v_bfe_u32 v150, v243, 16, 1
	v_add3_u32 v243, v243, v150, s43
	global_store_short_d16_hi v141, v243, s[4:5] offset:2176
	v_mul_f32_e32 v158, v84, v162
	v_fma_f32 v244, -v209, v158, v244
	v_bfe_u32 v158, v244, 16, 1
	v_add3_u32 v244, v244, v158, s43
	global_store_short_d16_hi v140, v244, s[4:5] offset:192
	v_mul_f32_e32 v159, v85, v163
	v_fma_f32 v245, -v209, v159, v245
	v_bfe_u32 v159, v245, 16, 1
	v_add3_u32 v245, v245, v159, s43
	global_store_short_d16_hi v140, v245, s[4:5] offset:2240
	v_mul_f32_e32 v160, v86, v164
	v_fma_f32 v246, -v209, v160, v246
	v_bfe_u32 v160, v246, 16, 1
	v_add3_u32 v246, v246, v160, s43
	global_store_short_d16_hi v141, v246, s[4:5] offset:192
	v_mul_f32_e32 v150, v87, v165
	v_fma_f32 v247, -v209, v150, v247
	v_bfe_u32 v150, v247, 16, 1
	v_add3_u32 v247, v247, v150, s43
	global_store_short_d16_hi v141, v247, s[4:5] offset:2240
	v_mul_f32_e32 v158, v68, v162
	v_fma_f32 v248, -v209, v158, v248
	v_bfe_u32 v158, v248, 16, 1
	v_add3_u32 v248, v248, v158, s43
	global_store_short_d16_hi v140, v248, s[4:5] offset:256
	v_mul_f32_e32 v159, v69, v163
	v_fma_f32 v249, -v209, v159, v249
	v_bfe_u32 v159, v249, 16, 1
	v_add3_u32 v249, v249, v159, s43
	global_store_short_d16_hi v140, v249, s[4:5] offset:2304
	v_mul_f32_e32 v160, v70, v164
	v_fma_f32 v250, -v209, v160, v250
	v_bfe_u32 v160, v250, 16, 1
	v_add3_u32 v250, v250, v160, s43
	global_store_short_d16_hi v141, v250, s[4:5] offset:256
	v_mul_f32_e32 v150, v71, v165
	v_fma_f32 v251, -v209, v150, v251
	v_bfe_u32 v150, v251, 16, 1
	v_add3_u32 v251, v251, v150, s43
	global_store_short_d16_hi v141, v251, s[4:5] offset:2304
	v_mul_f32_e32 v158, v52, v162
	v_fma_f32 v252, -v209, v158, v252
	v_bfe_u32 v158, v252, 16, 1
	v_add3_u32 v252, v252, v158, s43
	global_store_short_d16_hi v140, v252, s[4:5] offset:320
	v_mul_f32_e32 v159, v53, v163
	v_fma_f32 v253, -v209, v159, v253
	v_bfe_u32 v159, v253, 16, 1
	v_add3_u32 v253, v253, v159, s43
	global_store_short_d16_hi v140, v253, s[4:5] offset:2368
	v_mul_f32_e32 v160, v54, v164
	v_fma_f32 v254, -v209, v160, v254
	v_bfe_u32 v160, v254, 16, 1
	v_add3_u32 v254, v254, v160, s43
	global_store_short_d16_hi v141, v254, s[4:5] offset:320
	v_mul_f32_e32 v150, v55, v165
	v_fma_f32 v255, -v209, v150, v255
	v_bfe_u32 v150, v255, 16, 1
	v_add3_u32 v255, v255, v150, s43
	global_store_short_d16_hi v141, v255, s[4:5] offset:2368
	v_mul_f32_e32 v158, v36, v162
	v_fma_f32 v232, -v209, v158, v232
	v_bfe_u32 v158, v232, 16, 1
	v_add3_u32 v232, v232, v158, s43
	global_store_short_d16_hi v140, v232, s[4:5] offset:384
	v_mul_f32_e32 v159, v37, v163
	v_fma_f32 v233, -v209, v159, v233
	v_bfe_u32 v159, v233, 16, 1
	v_add3_u32 v233, v233, v159, s43
	global_store_short_d16_hi v140, v233, s[4:5] offset:2432
	v_mul_f32_e32 v160, v38, v164
	v_fma_f32 v234, -v209, v160, v234
	v_bfe_u32 v160, v234, 16, 1
	v_add3_u32 v234, v234, v160, s43
	global_store_short_d16_hi v141, v234, s[4:5] offset:384
	v_mul_f32_e32 v150, v39, v165
	v_fma_f32 v235, -v209, v150, v235
	v_bfe_u32 v150, v235, 16, 1
	v_add3_u32 v235, v235, v150, s43
	global_store_short_d16_hi v141, v235, s[4:5] offset:2432
	v_mul_f32_e32 v158, v20, v162
	v_fma_f32 v154, -v209, v158, v154
	v_bfe_u32 v158, v154, 16, 1
	v_add3_u32 v154, v154, v158, s43
	global_store_short_d16_hi v140, v154, s[4:5] offset:448
	v_mul_f32_e32 v159, v21, v163
	v_fma_f32 v155, -v209, v159, v155
	v_bfe_u32 v159, v155, 16, 1
	v_add3_u32 v155, v155, v159, s43
	global_store_short_d16_hi v140, v155, s[4:5] offset:2496
	v_mul_f32_e32 v160, v22, v164
	v_fma_f32 v156, -v209, v160, v156
	v_bfe_u32 v160, v156, 16, 1
	v_add3_u32 v156, v156, v160, s43
	global_store_short_d16_hi v141, v156, s[4:5] offset:448
	v_mul_f32_e32 v150, v23, v165
	v_fma_f32 v157, -v209, v150, v157
	v_bfe_u32 v150, v157, 16, 1
	v_add3_u32 v157, v157, v150, s43
	global_store_short_d16_hi v141, v157, s[4:5] offset:2496
	global_load_dwordx4 v[198:201], v128, s[96:97]
	s_add_u32 s96, s96, 0x1000
	s_addc_u32 s97, s97, 0
	global_load_dwordx4 v[202:205], v128, s[96:97]
	s_add_u32 s96, s96, 0x1000
	s_addc_u32 s97, s97, 0
	global_load_dwordx4 v[240:243], v128, s[96:97]
	s_add_u32 s96, s96, 0x1000
	s_addc_u32 s97, s97, 0
	global_load_dwordx4 v[244:247], v128, s[96:97]
	s_add_u32 s96, s96, 0x1000
	s_addc_u32 s97, s97, 0
	global_load_dwordx4 v[248:251], v128, s[96:97]
	s_add_u32 s96, s96, 0x1000
	s_addc_u32 s97, s97, 0
	global_load_dwordx4 v[252:255], v128, s[96:97]
	s_add_u32 s96, s96, 0x1000
	s_addc_u32 s97, s97, 0
	global_load_dwordx4 v[232:235], v128, s[96:97]
	s_add_u32 s96, s96, 0x1000
	s_addc_u32 s97, s97, 0
	global_load_dwordx4 v[154:157], v128, s[96:97]
	s_add_u32 s96, s96, 0x1000
	s_addc_u32 s97, s97, 0
	v_add_u32_e32 v140, 0x4000, v140
	s_waitcnt vmcnt(40)
	v_add_u32_e32 v141, 0x1000, v140
	v_mul_f32_e32 v158, v8, v137
	v_fma_f32 v166, -v209, v158, v166
	v_bfe_u32 v158, v166, 16, 1
	v_add3_u32 v166, v166, v158, s43
	global_store_short_d16_hi v140, v166, s[4:5]
	v_mul_f32_e32 v159, v9, v136
	v_fma_f32 v167, -v209, v159, v167
	v_bfe_u32 v159, v167, 16, 1
	v_add3_u32 v167, v167, v159, s43
	global_store_short_d16_hi v140, v167, s[4:5] offset:2048
	v_mul_f32_e32 v160, v10, v135
	v_fma_f32 v168, -v209, v160, v168
	v_bfe_u32 v160, v168, 16, 1
	v_add3_u32 v168, v168, v160, s43
	global_store_short_d16_hi v141, v168, s[4:5]
	v_mul_f32_e32 v150, v11, v134
	v_fma_f32 v169, -v209, v150, v169
	v_bfe_u32 v150, v169, 16, 1
	v_add3_u32 v169, v169, v150, s43
	global_store_short_d16_hi v141, v169, s[4:5] offset:2048
	v_mul_f32_e32 v158, v120, v137
	v_fma_f32 v170, -v209, v158, v170
	v_bfe_u32 v158, v170, 16, 1
	v_add3_u32 v170, v170, v158, s43
	global_store_short_d16_hi v140, v170, s[4:5] offset:64
	v_mul_f32_e32 v159, v121, v136
	v_fma_f32 v171, -v209, v159, v171
	v_bfe_u32 v159, v171, 16, 1
	v_add3_u32 v171, v171, v159, s43
	global_store_short_d16_hi v140, v171, s[4:5] offset:2112
	v_mul_f32_e32 v160, v122, v135
	v_fma_f32 v172, -v209, v160, v172
	v_bfe_u32 v160, v172, 16, 1
	v_add3_u32 v172, v172, v160, s43
	global_store_short_d16_hi v141, v172, s[4:5] offset:64
	v_mul_f32_e32 v150, v123, v134
	v_fma_f32 v173, -v209, v150, v173
	v_bfe_u32 v150, v173, 16, 1
	v_add3_u32 v173, v173, v150, s43
	global_store_short_d16_hi v141, v173, s[4:5] offset:2112
	v_mul_f32_e32 v158, v104, v137
	v_fma_f32 v174, -v209, v158, v174
	v_bfe_u32 v158, v174, 16, 1
	v_add3_u32 v174, v174, v158, s43
	global_store_short_d16_hi v140, v174, s[4:5] offset:128
	v_mul_f32_e32 v159, v105, v136
	v_fma_f32 v175, -v209, v159, v175
	v_bfe_u32 v159, v175, 16, 1
	v_add3_u32 v175, v175, v159, s43
	global_store_short_d16_hi v140, v175, s[4:5] offset:2176
	v_mul_f32_e32 v160, v106, v135
	v_fma_f32 v176, -v209, v160, v176
	v_bfe_u32 v160, v176, 16, 1
	v_add3_u32 v176, v176, v160, s43
	global_store_short_d16_hi v141, v176, s[4:5] offset:128
	v_mul_f32_e32 v150, v107, v134
	v_fma_f32 v177, -v209, v150, v177
	v_bfe_u32 v150, v177, 16, 1
	v_add3_u32 v177, v177, v150, s43
	global_store_short_d16_hi v141, v177, s[4:5] offset:2176
	v_mul_f32_e32 v158, v88, v137
	v_fma_f32 v178, -v209, v158, v178
	v_bfe_u32 v158, v178, 16, 1
	v_add3_u32 v178, v178, v158, s43
	global_store_short_d16_hi v140, v178, s[4:5] offset:192
	v_mul_f32_e32 v159, v89, v136
	v_fma_f32 v179, -v209, v159, v179
	v_bfe_u32 v159, v179, 16, 1
	v_add3_u32 v179, v179, v159, s43
	global_store_short_d16_hi v140, v179, s[4:5] offset:2240
	v_mul_f32_e32 v160, v90, v135
	v_fma_f32 v180, -v209, v160, v180
	v_bfe_u32 v160, v180, 16, 1
	v_add3_u32 v180, v180, v160, s43
	global_store_short_d16_hi v141, v180, s[4:5] offset:192
	v_mul_f32_e32 v150, v91, v134
	v_fma_f32 v181, -v209, v150, v181
	v_bfe_u32 v150, v181, 16, 1
	v_add3_u32 v181, v181, v150, s43
	global_store_short_d16_hi v141, v181, s[4:5] offset:2240
	v_mul_f32_e32 v158, v72, v137
	v_fma_f32 v182, -v209, v158, v182
	v_bfe_u32 v158, v182, 16, 1
	v_add3_u32 v182, v182, v158, s43
	global_store_short_d16_hi v140, v182, s[4:5] offset:256
	v_mul_f32_e32 v159, v73, v136
	v_fma_f32 v183, -v209, v159, v183
	v_bfe_u32 v159, v183, 16, 1
	v_add3_u32 v183, v183, v159, s43
	global_store_short_d16_hi v140, v183, s[4:5] offset:2304
	v_mul_f32_e32 v160, v74, v135
	v_fma_f32 v184, -v209, v160, v184
	v_bfe_u32 v160, v184, 16, 1
	v_add3_u32 v184, v184, v160, s43
	global_store_short_d16_hi v141, v184, s[4:5] offset:256
	v_mul_f32_e32 v150, v75, v134
	v_fma_f32 v185, -v209, v150, v185
	v_bfe_u32 v150, v185, 16, 1
	v_add3_u32 v185, v185, v150, s43
	global_store_short_d16_hi v141, v185, s[4:5] offset:2304
	v_mul_f32_e32 v158, v56, v137
	v_fma_f32 v186, -v209, v158, v186
	v_bfe_u32 v158, v186, 16, 1
	v_add3_u32 v186, v186, v158, s43
	global_store_short_d16_hi v140, v186, s[4:5] offset:320
	v_mul_f32_e32 v159, v57, v136
	v_fma_f32 v187, -v209, v159, v187
	v_bfe_u32 v159, v187, 16, 1
	v_add3_u32 v187, v187, v159, s43
	global_store_short_d16_hi v140, v187, s[4:5] offset:2368
	v_mul_f32_e32 v160, v58, v135
	v_fma_f32 v188, -v209, v160, v188
	v_bfe_u32 v160, v188, 16, 1
	v_add3_u32 v188, v188, v160, s43
	global_store_short_d16_hi v141, v188, s[4:5] offset:320
	v_mul_f32_e32 v150, v59, v134
	v_fma_f32 v189, -v209, v150, v189
	v_bfe_u32 v150, v189, 16, 1
	v_add3_u32 v189, v189, v150, s43
	global_store_short_d16_hi v141, v189, s[4:5] offset:2368
	v_mul_f32_e32 v158, v40, v137
	v_fma_f32 v190, -v209, v158, v190
	v_bfe_u32 v158, v190, 16, 1
	v_add3_u32 v190, v190, v158, s43
	global_store_short_d16_hi v140, v190, s[4:5] offset:384
	v_mul_f32_e32 v159, v41, v136
	v_fma_f32 v191, -v209, v159, v191
	v_bfe_u32 v159, v191, 16, 1
	v_add3_u32 v191, v191, v159, s43
	global_store_short_d16_hi v140, v191, s[4:5] offset:2432
	v_mul_f32_e32 v160, v42, v135
	v_fma_f32 v192, -v209, v160, v192
	v_bfe_u32 v160, v192, 16, 1
	v_add3_u32 v192, v192, v160, s43
	global_store_short_d16_hi v141, v192, s[4:5] offset:384
	v_mul_f32_e32 v150, v43, v134
	v_fma_f32 v193, -v209, v150, v193
	v_bfe_u32 v150, v193, 16, 1
	v_add3_u32 v193, v193, v150, s43
	global_store_short_d16_hi v141, v193, s[4:5] offset:2432
	v_mul_f32_e32 v158, v24, v137
	v_fma_f32 v194, -v209, v158, v194
	v_bfe_u32 v158, v194, 16, 1
	v_add3_u32 v194, v194, v158, s43
	global_store_short_d16_hi v140, v194, s[4:5] offset:448
	v_mul_f32_e32 v159, v25, v136
	v_fma_f32 v195, -v209, v159, v195
	v_bfe_u32 v159, v195, 16, 1
	v_add3_u32 v195, v195, v159, s43
	global_store_short_d16_hi v140, v195, s[4:5] offset:2496
	v_mul_f32_e32 v160, v26, v135
	v_fma_f32 v196, -v209, v160, v196
	v_bfe_u32 v160, v196, 16, 1
	v_add3_u32 v196, v196, v160, s43
	global_store_short_d16_hi v141, v196, s[4:5] offset:448
	v_mul_f32_e32 v150, v27, v134
	v_fma_f32 v197, -v209, v150, v197
	v_bfe_u32 v150, v197, 16, 1
	v_add3_u32 v197, v197, v150, s43
	global_store_short_d16_hi v141, v197, s[4:5] offset:2496
	v_add_u32_e32 v140, 0x4000, v140
	s_waitcnt vmcnt(32)
	v_add_u32_e32 v141, 0x1000, v140
	v_mul_f32_e32 v158, v12, v133
	v_fma_f32 v198, -v209, v158, v198
	v_bfe_u32 v158, v198, 16, 1
	v_add3_u32 v198, v198, v158, s43
	global_store_short_d16_hi v140, v198, s[4:5]
	v_mul_f32_e32 v159, v13, v132
	v_fma_f32 v199, -v209, v159, v199
	v_bfe_u32 v159, v199, 16, 1
	v_add3_u32 v199, v199, v159, s43
	global_store_short_d16_hi v140, v199, s[4:5] offset:2048
	v_mul_f32_e32 v160, v14, v131
	v_fma_f32 v200, -v209, v160, v200
	v_bfe_u32 v160, v200, 16, 1
	v_add3_u32 v200, v200, v160, s43
	global_store_short_d16_hi v141, v200, s[4:5]
	v_mul_f32_e32 v150, v15, v130
	v_fma_f32 v201, -v209, v150, v201
	v_bfe_u32 v150, v201, 16, 1
	v_add3_u32 v201, v201, v150, s43
	global_store_short_d16_hi v141, v201, s[4:5] offset:2048
	v_mul_f32_e32 v158, v124, v133
	v_fma_f32 v202, -v209, v158, v202
	v_bfe_u32 v158, v202, 16, 1
	v_add3_u32 v202, v202, v158, s43
	global_store_short_d16_hi v140, v202, s[4:5] offset:64
	v_mul_f32_e32 v159, v125, v132
	v_fma_f32 v203, -v209, v159, v203
	v_bfe_u32 v159, v203, 16, 1
	v_add3_u32 v203, v203, v159, s43
	global_store_short_d16_hi v140, v203, s[4:5] offset:2112
	v_mul_f32_e32 v160, v126, v131
	v_fma_f32 v204, -v209, v160, v204
	v_bfe_u32 v160, v204, 16, 1
	v_add3_u32 v204, v204, v160, s43
	global_store_short_d16_hi v141, v204, s[4:5] offset:64
	v_mul_f32_e32 v150, v127, v130
	v_fma_f32 v205, -v209, v150, v205
	v_bfe_u32 v150, v205, 16, 1
	v_add3_u32 v205, v205, v150, s43
	global_store_short_d16_hi v141, v205, s[4:5] offset:2112
	v_mul_f32_e32 v158, v108, v133
	v_fma_f32 v240, -v209, v158, v240
	v_bfe_u32 v158, v240, 16, 1
	v_add3_u32 v240, v240, v158, s43
	global_store_short_d16_hi v140, v240, s[4:5] offset:128
	v_mul_f32_e32 v159, v109, v132
	v_fma_f32 v241, -v209, v159, v241
	v_bfe_u32 v159, v241, 16, 1
	v_add3_u32 v241, v241, v159, s43
	global_store_short_d16_hi v140, v241, s[4:5] offset:2176
	v_mul_f32_e32 v160, v110, v131
	v_fma_f32 v242, -v209, v160, v242
	v_bfe_u32 v160, v242, 16, 1
	v_add3_u32 v242, v242, v160, s43
	global_store_short_d16_hi v141, v242, s[4:5] offset:128
	v_mul_f32_e32 v150, v111, v130
	v_fma_f32 v243, -v209, v150, v243
	v_bfe_u32 v150, v243, 16, 1
	v_add3_u32 v243, v243, v150, s43
	global_store_short_d16_hi v141, v243, s[4:5] offset:2176
	v_mul_f32_e32 v158, v92, v133
	v_fma_f32 v244, -v209, v158, v244
	v_bfe_u32 v158, v244, 16, 1
	v_add3_u32 v244, v244, v158, s43
	global_store_short_d16_hi v140, v244, s[4:5] offset:192
	v_mul_f32_e32 v159, v93, v132
	v_fma_f32 v245, -v209, v159, v245
	v_bfe_u32 v159, v245, 16, 1
	v_add3_u32 v245, v245, v159, s43
	global_store_short_d16_hi v140, v245, s[4:5] offset:2240
	v_mul_f32_e32 v160, v94, v131
	v_fma_f32 v246, -v209, v160, v246
	v_bfe_u32 v160, v246, 16, 1
	v_add3_u32 v246, v246, v160, s43
	global_store_short_d16_hi v141, v246, s[4:5] offset:192
	v_mul_f32_e32 v150, v95, v130
	v_fma_f32 v247, -v209, v150, v247
	v_bfe_u32 v150, v247, 16, 1
	v_add3_u32 v247, v247, v150, s43
	global_store_short_d16_hi v141, v247, s[4:5] offset:2240
	v_mul_f32_e32 v158, v76, v133
	v_fma_f32 v248, -v209, v158, v248
	v_bfe_u32 v158, v248, 16, 1
	v_add3_u32 v248, v248, v158, s43
	global_store_short_d16_hi v140, v248, s[4:5] offset:256
	v_mul_f32_e32 v159, v77, v132
	v_fma_f32 v249, -v209, v159, v249
	v_bfe_u32 v159, v249, 16, 1
	v_add3_u32 v249, v249, v159, s43
	global_store_short_d16_hi v140, v249, s[4:5] offset:2304
	v_mul_f32_e32 v160, v78, v131
	v_fma_f32 v250, -v209, v160, v250
	v_bfe_u32 v160, v250, 16, 1
	v_add3_u32 v250, v250, v160, s43
	global_store_short_d16_hi v141, v250, s[4:5] offset:256
	v_mul_f32_e32 v150, v79, v130
	v_fma_f32 v251, -v209, v150, v251
	v_bfe_u32 v150, v251, 16, 1
	v_add3_u32 v251, v251, v150, s43
	global_store_short_d16_hi v141, v251, s[4:5] offset:2304
	v_mul_f32_e32 v158, v60, v133
	v_fma_f32 v252, -v209, v158, v252
	v_bfe_u32 v158, v252, 16, 1
	v_add3_u32 v252, v252, v158, s43
	global_store_short_d16_hi v140, v252, s[4:5] offset:320
	v_mul_f32_e32 v159, v61, v132
	v_fma_f32 v253, -v209, v159, v253
	v_bfe_u32 v159, v253, 16, 1
	v_add3_u32 v253, v253, v159, s43
	global_store_short_d16_hi v140, v253, s[4:5] offset:2368
	v_mul_f32_e32 v160, v62, v131
	v_fma_f32 v254, -v209, v160, v254
	v_bfe_u32 v160, v254, 16, 1
	v_add3_u32 v254, v254, v160, s43
	global_store_short_d16_hi v141, v254, s[4:5] offset:320
	v_mul_f32_e32 v150, v63, v130
	v_fma_f32 v255, -v209, v150, v255
	v_bfe_u32 v150, v255, 16, 1
	v_add3_u32 v255, v255, v150, s43
	global_store_short_d16_hi v141, v255, s[4:5] offset:2368
	v_mul_f32_e32 v158, v44, v133
	v_fma_f32 v232, -v209, v158, v232
	v_bfe_u32 v158, v232, 16, 1
	v_add3_u32 v232, v232, v158, s43
	global_store_short_d16_hi v140, v232, s[4:5] offset:384
	v_mul_f32_e32 v159, v45, v132
	v_fma_f32 v233, -v209, v159, v233
	v_bfe_u32 v159, v233, 16, 1
	v_add3_u32 v233, v233, v159, s43
	global_store_short_d16_hi v140, v233, s[4:5] offset:2432
	v_mul_f32_e32 v160, v46, v131
	v_fma_f32 v234, -v209, v160, v234
	v_bfe_u32 v160, v234, 16, 1
	v_add3_u32 v234, v234, v160, s43
	global_store_short_d16_hi v141, v234, s[4:5] offset:384
	v_mul_f32_e32 v150, v47, v130
	v_fma_f32 v235, -v209, v150, v235
	v_bfe_u32 v150, v235, 16, 1
	v_add3_u32 v235, v235, v150, s43
	global_store_short_d16_hi v141, v235, s[4:5] offset:2432
	v_mul_f32_e32 v158, v28, v133
	v_fma_f32 v154, -v209, v158, v154
	v_bfe_u32 v158, v154, 16, 1
	v_add3_u32 v154, v154, v158, s43
	global_store_short_d16_hi v140, v154, s[4:5] offset:448
	v_mul_f32_e32 v159, v29, v132
	v_fma_f32 v155, -v209, v159, v155
	v_bfe_u32 v159, v155, 16, 1
	v_add3_u32 v155, v155, v159, s43
	global_store_short_d16_hi v140, v155, s[4:5] offset:2496
	v_mul_f32_e32 v160, v30, v131
	v_fma_f32 v156, -v209, v160, v156
	v_bfe_u32 v160, v156, 16, 1
	v_add3_u32 v156, v156, v160, s43
	global_store_short_d16_hi v141, v156, s[4:5] offset:448
	v_mul_f32_e32 v150, v31, v130
	v_fma_f32 v157, -v209, v150, v157
	v_bfe_u32 v150, v157, 16, 1
	v_add3_u32 v157, v157, v150, s43
	global_store_short_d16_hi v141, v157, s[4:5] offset:2496
	s_branch .LBB0_901
